# phase_mod item loop rewritten (64-column items, all weight rows in flight); kernel-start L2 write-back issued by wave 0 only
# speedup vs baseline: 1.0220x; 1.0083x over previous
.LBB0_5:
	s_or_b64 exec, exec, s[0:1]
	s_movk_i32 s0, 0x2000
	s_lshr_b32 s25, s22, 6
	v_cmp_gt_i32_e32 vcc, s0, v2
	s_cmp_lg_u32 s25, 0
	s_cbranch_scc1 .Lks_nowb
	buffer_wbl2 sc1
.Lks_nowb:
	s_waitcnt vmcnt(0) lgkmcnt(0)
	buffer_inv sc1
	s_barrier
	s_and_saveexec_b64 s[0:1], vcc
	s_cbranch_execz .LBB0_8
	v_mov_b32_e32 v3, 0xf000
	global_load_dwordx2 v[4:5], v3, s[46:47] offset:8
	s_lshl_b32 s2, s25, 8
	s_add_i32 s2, s2, 16
	v_lshl_add_u32 v3, v192, 2, s2
	v_readlane_b32 s2, v252, 2
	v_mov_b32_e32 v193, 0
	v_readlane_b32 s3, v252, 3
	s_mov_b32 s4, s2
	s_ashr_i32 s5, s2, 31
	v_writelane_b32 v252, s2, 2
	v_lshl_add_u64 v[6:7], v[192:193], 0, s[4:5]
	v_add_u32_e32 v3, 0x11170, v3
	v_add_u32_e32 v8, 0xfffffe00, v2
	v_writelane_b32 v252, s3, 3
	v_lshlrev_b64 v[6:7], 2, v[6:7]
	s_mov_b64 s[2:3], 0
	s_mov_b64 s[4:5], 0x800
	s_movk_i32 s6, 0x1dff
	s_waitcnt vmcnt(0)
	v_readfirstlane_b32 s8, v4
	v_readfirstlane_b32 s9, v5
	s_nop 1
	v_lshl_add_u64 v[10:11], s[8:9], 0, v[6:7]
	global_load_dword v12, v[10:11], off
	global_load_dword v13, v[10:11], off offset:2048
	v_add_co_u32_e32 v10, vcc, 0x1000, v10
	s_nop 1
	v_addc_co_u32_e32 v11, vcc, 0, v11, vcc
	global_load_dword v14, v[10:11], off
	global_load_dword v15, v[10:11], off offset:2048
	v_add_co_u32_e32 v10, vcc, 0x1000, v10
	s_nop 1
	v_addc_co_u32_e32 v11, vcc, 0, v11, vcc
	global_load_dword v16, v[10:11], off
	global_load_dword v17, v[10:11], off offset:2048
	v_add_co_u32_e32 v10, vcc, 0x1000, v10
	s_nop 1
	v_addc_co_u32_e32 v11, vcc, 0, v11, vcc
	global_load_dword v18, v[10:11], off
	global_load_dword v19, v[10:11], off offset:2048
	v_add_co_u32_e32 v10, vcc, 0x1000, v10
	s_nop 1
	v_addc_co_u32_e32 v11, vcc, 0, v11, vcc
	global_load_dword v20, v[10:11], off
	global_load_dword v21, v[10:11], off offset:2048
	v_add_co_u32_e32 v10, vcc, 0x1000, v10
	s_nop 1
	v_addc_co_u32_e32 v11, vcc, 0, v11, vcc
	global_load_dword v22, v[10:11], off
	global_load_dword v23, v[10:11], off offset:2048
	v_add_co_u32_e32 v10, vcc, 0x1000, v10
	s_nop 1
	v_addc_co_u32_e32 v11, vcc, 0, v11, vcc
	global_load_dword v24, v[10:11], off
	global_load_dword v25, v[10:11], off offset:2048
	v_add_co_u32_e32 v10, vcc, 0x1000, v10
	s_nop 1
	v_addc_co_u32_e32 v11, vcc, 0, v11, vcc
	global_load_dword v26, v[10:11], off
	global_load_dword v27, v[10:11], off offset:2048
	s_waitcnt vmcnt(14)
	v_mul_f32_e32 v6, 0xbfb8aa3b, v12
	v_mul_f32_e32 v7, 0xbfb8aa3b, v13
	v_exp_f32_e32 v6, v6
	v_exp_f32_e32 v7, v7
	s_nop 0
	v_add_f32_e32 v6, 1.0, v6
	v_add_f32_e32 v7, 1.0, v7
	v_rcp_f32_e32 v6, v6
	v_rcp_f32_e32 v7, v7
	s_nop 0
	v_mul_f32_e32 v12, v12, v6
	v_mul_f32_e32 v13, v13, v7
	ds_write_b32 v3, v12
	ds_write_b32 v3, v13 offset:2048
	s_waitcnt vmcnt(12)
	v_mul_f32_e32 v6, 0xbfb8aa3b, v14
	v_mul_f32_e32 v7, 0xbfb8aa3b, v15
	v_exp_f32_e32 v6, v6
	v_exp_f32_e32 v7, v7
	s_nop 0
	v_add_f32_e32 v6, 1.0, v6
	v_add_f32_e32 v7, 1.0, v7
	v_rcp_f32_e32 v6, v6
	v_rcp_f32_e32 v7, v7
	s_nop 0
	v_mul_f32_e32 v14, v14, v6
	v_mul_f32_e32 v15, v15, v7
	ds_write_b32 v3, v14 offset:4096
	ds_write_b32 v3, v15 offset:6144
	s_waitcnt vmcnt(10)
	v_mul_f32_e32 v6, 0xbfb8aa3b, v16
	v_mul_f32_e32 v7, 0xbfb8aa3b, v17
	v_exp_f32_e32 v6, v6
	v_exp_f32_e32 v7, v7
	s_nop 0
	v_add_f32_e32 v6, 1.0, v6
	v_add_f32_e32 v7, 1.0, v7
	v_rcp_f32_e32 v6, v6
	v_rcp_f32_e32 v7, v7
	s_nop 0
	v_mul_f32_e32 v16, v16, v6
	v_mul_f32_e32 v17, v17, v7
	ds_write_b32 v3, v16 offset:8192
	ds_write_b32 v3, v17 offset:10240
	s_waitcnt vmcnt(8)
	v_mul_f32_e32 v6, 0xbfb8aa3b, v18
	v_mul_f32_e32 v7, 0xbfb8aa3b, v19
	v_exp_f32_e32 v6, v6
	v_exp_f32_e32 v7, v7
	s_nop 0
	v_add_f32_e32 v6, 1.0, v6
	v_add_f32_e32 v7, 1.0, v7
	v_rcp_f32_e32 v6, v6
	v_rcp_f32_e32 v7, v7
	s_nop 0
	v_mul_f32_e32 v18, v18, v6
	v_mul_f32_e32 v19, v19, v7
	ds_write_b32 v3, v18 offset:12288
	ds_write_b32 v3, v19 offset:14336
	s_waitcnt vmcnt(6)
	v_mul_f32_e32 v6, 0xbfb8aa3b, v20
	v_mul_f32_e32 v7, 0xbfb8aa3b, v21
	v_exp_f32_e32 v6, v6
	v_exp_f32_e32 v7, v7
	s_nop 0
	v_add_f32_e32 v6, 1.0, v6
	v_add_f32_e32 v7, 1.0, v7
	v_rcp_f32_e32 v6, v6
	v_rcp_f32_e32 v7, v7
	s_nop 0
	v_mul_f32_e32 v20, v20, v6
	v_mul_f32_e32 v21, v21, v7
	ds_write_b32 v3, v20 offset:16384
	ds_write_b32 v3, v21 offset:18432
	s_waitcnt vmcnt(4)
	v_mul_f32_e32 v6, 0xbfb8aa3b, v22
	v_mul_f32_e32 v7, 0xbfb8aa3b, v23
	v_exp_f32_e32 v6, v6
	v_exp_f32_e32 v7, v7
	s_nop 0
	v_add_f32_e32 v6, 1.0, v6
	v_add_f32_e32 v7, 1.0, v7
	v_rcp_f32_e32 v6, v6
	v_rcp_f32_e32 v7, v7
	s_nop 0
	v_mul_f32_e32 v22, v22, v6
	v_mul_f32_e32 v23, v23, v7
	ds_write_b32 v3, v22 offset:20480
	ds_write_b32 v3, v23 offset:22528
	s_waitcnt vmcnt(2)
	v_mul_f32_e32 v6, 0xbfb8aa3b, v24
	v_mul_f32_e32 v7, 0xbfb8aa3b, v25
	v_exp_f32_e32 v6, v6
	v_exp_f32_e32 v7, v7
	s_nop 0
	v_add_f32_e32 v6, 1.0, v6
	v_add_f32_e32 v7, 1.0, v7
	v_rcp_f32_e32 v6, v6
	v_rcp_f32_e32 v7, v7
	s_nop 0
	v_mul_f32_e32 v24, v24, v6
	v_mul_f32_e32 v25, v25, v7
	ds_write_b32 v3, v24 offset:24576
	ds_write_b32 v3, v25 offset:26624
	s_waitcnt vmcnt(0)
	v_mul_f32_e32 v6, 0xbfb8aa3b, v26
	v_mul_f32_e32 v7, 0xbfb8aa3b, v27
	v_exp_f32_e32 v6, v6
	v_exp_f32_e32 v7, v7
	s_nop 0
	v_add_f32_e32 v6, 1.0, v6
	v_add_f32_e32 v7, 1.0, v7
	v_rcp_f32_e32 v6, v6
	v_rcp_f32_e32 v7, v7
	s_nop 0
	v_mul_f32_e32 v26, v26, v6
	v_mul_f32_e32 v27, v27, v7
	ds_write_b32 v3, v26 offset:28672
	ds_write_b32 v3, v27 offset:30720
.LBB0_8:
	s_or_b64 exec, exec, s[0:1]
	s_cmpk_gt_i32 s92, 0xbf
	s_waitcnt lgkmcnt(0)
	s_barrier
	s_cbranch_scc1 .LBB0_19
	s_add_u32 s2, s46, 0xf010
	s_addc_u32 s3, s47, 0
	v_mov_b32_e32 v129, 0
	global_load_dwordx4 v[4:7], v129, s[2:3]
	s_cmpk_gt_i32 s92, 0x5f
	s_cselect_b32 s24, 1, 0
	s_mul_i32 s0, s24, 0x60
	s_sub_i32 s0, s92, s0
	s_lshl_b32 s14, s0, 8
	v_and_b32_e32 v8, 31, v192
	v_ashrrev_i32_e32 v9, 5, v2
	v_lshlrev_b32_e32 v10, 3, v8
	v_mul_u32_u24_e32 v11, 0x180000, v9
	v_add3_u32 v12, v11, v10, s14
	v_lshlrev_b32_e32 v13, 8, v9
	v_add_u32_e32 v13, 0x11180, v13
	v_lshlrev_b32_e32 v14, 11, v9
	v_add_u32_e32 v14, v14, v10
	v_add_u32_e32 v14, 0x19180, v14
	v_lshrrev_b32_e32 v15, 6, v2
	v_and_b32_e32 v3, 63, v2
	v_lshlrev_b32_e32 v232, 8, v15
	v_lshl_add_u32 v232, v3, 2, v232
	v_add_u32_e32 v232, 0x19180, v232
	v_mul_u32_u24_e32 v233, 0x6000, v15
	v_lshl_add_u32 v233, v3, 2, v233
	v_lshlrev_b32_e32 v234, 2, v3
	v_mov_b32_e32 v235, 0
	s_waitcnt vmcnt(0)
	v_readfirstlane_b32 s4, v4
	v_readfirstlane_b32 s5, v5
	v_readfirstlane_b32 s16, v6
	v_readfirstlane_b32 s17, v7
	s_mul_i32 s0, s24, 0x1800000
	s_add_u32 s8, s4, s0
	s_addc_u32 s9, s5, 0
	s_mul_i32 s0, s24, 0x6000
	s_add_u32 s0, s0, s14
	s_add_u32 s18, s16, s0
	s_addc_u32 s19, s17, 0
	s_mul_i32 s0, s24, 0x30000
	s_add_u32 s0, s0, s14
	s_add_u32 s0, s0, 0x10000
	s_add_u32 s10, s46, s0
	s_addc_u32 s11, s47, 0
	s_cmp_eq_u64 s[16:17], 0
	s_cbranch_scc1 .Lmod_nobias
	global_load_dword v235, v234, s[18:19]
.Lmod_nobias:
	ds_read_b128 v[16:19], v13 offset:0
	ds_read_b128 v[20:23], v13 offset:4096
	ds_read_b128 v[24:27], v13 offset:8192
	ds_read_b128 v[28:31], v13 offset:12288
	ds_read_b128 v[32:35], v13 offset:16384
	ds_read_b128 v[36:39], v13 offset:20480
	ds_read_b128 v[40:43], v13 offset:24576
	ds_read_b128 v[44:47], v13 offset:28672
	global_load_dwordx2 v[64:65], v12, s[8:9]
	s_add_u32 s8, s8, 0x6000
	s_addc_u32 s9, s9, 0
	global_load_dwordx2 v[66:67], v12, s[8:9]
	s_add_u32 s8, s8, 0x6000
	s_addc_u32 s9, s9, 0
	global_load_dwordx2 v[68:69], v12, s[8:9]
	s_add_u32 s8, s8, 0x6000
	s_addc_u32 s9, s9, 0
	global_load_dwordx2 v[70:71], v12, s[8:9]
	s_add_u32 s8, s8, 0x6000
	s_addc_u32 s9, s9, 0
	global_load_dwordx2 v[72:73], v12, s[8:9]
	s_add_u32 s8, s8, 0x6000
	s_addc_u32 s9, s9, 0
	global_load_dwordx2 v[74:75], v12, s[8:9]
	s_add_u32 s8, s8, 0x6000
	s_addc_u32 s9, s9, 0
	global_load_dwordx2 v[76:77], v12, s[8:9]
	s_add_u32 s8, s8, 0x6000
	s_addc_u32 s9, s9, 0
	global_load_dwordx2 v[78:79], v12, s[8:9]
	s_add_u32 s8, s8, 0x6000
	s_addc_u32 s9, s9, 0
	global_load_dwordx2 v[80:81], v12, s[8:9]
	s_add_u32 s8, s8, 0x6000
	s_addc_u32 s9, s9, 0
	global_load_dwordx2 v[82:83], v12, s[8:9]
	s_add_u32 s8, s8, 0x6000
	s_addc_u32 s9, s9, 0
	global_load_dwordx2 v[84:85], v12, s[8:9]
	s_add_u32 s8, s8, 0x6000
	s_addc_u32 s9, s9, 0
	global_load_dwordx2 v[86:87], v12, s[8:9]
	s_add_u32 s8, s8, 0x6000
	s_addc_u32 s9, s9, 0
	global_load_dwordx2 v[88:89], v12, s[8:9]
	s_add_u32 s8, s8, 0x6000
	s_addc_u32 s9, s9, 0
	global_load_dwordx2 v[90:91], v12, s[8:9]
	s_add_u32 s8, s8, 0x6000
	s_addc_u32 s9, s9, 0
	global_load_dwordx2 v[92:93], v12, s[8:9]
	s_add_u32 s8, s8, 0x6000
	s_addc_u32 s9, s9, 0
	global_load_dwordx2 v[94:95], v12, s[8:9]
	s_add_u32 s8, s8, 0x6000
	s_addc_u32 s9, s9, 0
	global_load_dwordx2 v[96:97], v12, s[8:9]
	s_add_u32 s8, s8, 0x6000
	s_addc_u32 s9, s9, 0
	global_load_dwordx2 v[98:99], v12, s[8:9]
	s_add_u32 s8, s8, 0x6000
	s_addc_u32 s9, s9, 0
	global_load_dwordx2 v[100:101], v12, s[8:9]
	s_add_u32 s8, s8, 0x6000
	s_addc_u32 s9, s9, 0
	global_load_dwordx2 v[102:103], v12, s[8:9]
	s_add_u32 s8, s8, 0x6000
	s_addc_u32 s9, s9, 0
	global_load_dwordx2 v[104:105], v12, s[8:9]
	s_add_u32 s8, s8, 0x6000
	s_addc_u32 s9, s9, 0
	global_load_dwordx2 v[106:107], v12, s[8:9]
	s_add_u32 s8, s8, 0x6000
	s_addc_u32 s9, s9, 0
	global_load_dwordx2 v[108:109], v12, s[8:9]
	s_add_u32 s8, s8, 0x6000
	s_addc_u32 s9, s9, 0
	global_load_dwordx2 v[110:111], v12, s[8:9]
	s_add_u32 s8, s8, 0x6000
	s_addc_u32 s9, s9, 0
	global_load_dwordx2 v[112:113], v12, s[8:9]
	s_add_u32 s8, s8, 0x6000
	s_addc_u32 s9, s9, 0
	global_load_dwordx2 v[114:115], v12, s[8:9]
	s_add_u32 s8, s8, 0x6000
	s_addc_u32 s9, s9, 0
	global_load_dwordx2 v[116:117], v12, s[8:9]
	s_add_u32 s8, s8, 0x6000
	s_addc_u32 s9, s9, 0
	global_load_dwordx2 v[118:119], v12, s[8:9]
	s_add_u32 s8, s8, 0x6000
	s_addc_u32 s9, s9, 0
	global_load_dwordx2 v[120:121], v12, s[8:9]
	s_add_u32 s8, s8, 0x6000
	s_addc_u32 s9, s9, 0
	global_load_dwordx2 v[122:123], v12, s[8:9]
	s_add_u32 s8, s8, 0x6000
	s_addc_u32 s9, s9, 0
	global_load_dwordx2 v[124:125], v12, s[8:9]
	s_add_u32 s8, s8, 0x6000
	s_addc_u32 s9, s9, 0
	global_load_dwordx2 v[126:127], v12, s[8:9]
	s_add_u32 s8, s8, 0x6000
	s_addc_u32 s9, s9, 0
	global_load_dwordx2 v[128:129], v12, s[8:9]
	s_add_u32 s8, s8, 0x6000
	s_addc_u32 s9, s9, 0
	global_load_dwordx2 v[130:131], v12, s[8:9]
	s_add_u32 s8, s8, 0x6000
	s_addc_u32 s9, s9, 0
	global_load_dwordx2 v[132:133], v12, s[8:9]
	s_add_u32 s8, s8, 0x6000
	s_addc_u32 s9, s9, 0
	global_load_dwordx2 v[134:135], v12, s[8:9]
	s_add_u32 s8, s8, 0x6000
	s_addc_u32 s9, s9, 0
	global_load_dwordx2 v[136:137], v12, s[8:9]
	s_add_u32 s8, s8, 0x6000
	s_addc_u32 s9, s9, 0
	global_load_dwordx2 v[138:139], v12, s[8:9]
	s_add_u32 s8, s8, 0x6000
	s_addc_u32 s9, s9, 0
	global_load_dwordx2 v[140:141], v12, s[8:9]
	s_add_u32 s8, s8, 0x6000
	s_addc_u32 s9, s9, 0
	global_load_dwordx2 v[142:143], v12, s[8:9]
	s_add_u32 s8, s8, 0x6000
	s_addc_u32 s9, s9, 0
	global_load_dwordx2 v[144:145], v12, s[8:9]
	s_add_u32 s8, s8, 0x6000
	s_addc_u32 s9, s9, 0
	global_load_dwordx2 v[146:147], v12, s[8:9]
	s_add_u32 s8, s8, 0x6000
	s_addc_u32 s9, s9, 0
	global_load_dwordx2 v[148:149], v12, s[8:9]
	s_add_u32 s8, s8, 0x6000
	s_addc_u32 s9, s9, 0
	global_load_dwordx2 v[150:151], v12, s[8:9]
	s_add_u32 s8, s8, 0x6000
	s_addc_u32 s9, s9, 0
	global_load_dwordx2 v[152:153], v12, s[8:9]
	s_add_u32 s8, s8, 0x6000
	s_addc_u32 s9, s9, 0
	global_load_dwordx2 v[154:155], v12, s[8:9]
	s_add_u32 s8, s8, 0x6000
	s_addc_u32 s9, s9, 0
	global_load_dwordx2 v[156:157], v12, s[8:9]
	s_add_u32 s8, s8, 0x6000
	s_addc_u32 s9, s9, 0
	global_load_dwordx2 v[158:159], v12, s[8:9]
	s_add_u32 s8, s8, 0x6000
	s_addc_u32 s9, s9, 0
	global_load_dwordx2 v[160:161], v12, s[8:9]
	s_add_u32 s8, s8, 0x6000
	s_addc_u32 s9, s9, 0
	global_load_dwordx2 v[162:163], v12, s[8:9]
	s_add_u32 s8, s8, 0x6000
	s_addc_u32 s9, s9, 0
	global_load_dwordx2 v[164:165], v12, s[8:9]
	s_add_u32 s8, s8, 0x6000
	s_addc_u32 s9, s9, 0
	global_load_dwordx2 v[166:167], v12, s[8:9]
	s_add_u32 s8, s8, 0x6000
	s_addc_u32 s9, s9, 0
	global_load_dwordx2 v[168:169], v12, s[8:9]
	s_add_u32 s8, s8, 0x6000
	s_addc_u32 s9, s9, 0
	global_load_dwordx2 v[170:171], v12, s[8:9]
	s_add_u32 s8, s8, 0x6000
	s_addc_u32 s9, s9, 0
	global_load_dwordx2 v[172:173], v12, s[8:9]
	s_add_u32 s8, s8, 0x6000
	s_addc_u32 s9, s9, 0
	global_load_dwordx2 v[174:175], v12, s[8:9]
	s_add_u32 s8, s8, 0x6000
	s_addc_u32 s9, s9, 0
	global_load_dwordx2 v[176:177], v12, s[8:9]
	s_add_u32 s8, s8, 0x6000
	s_addc_u32 s9, s9, 0
	global_load_dwordx2 v[178:179], v12, s[8:9]
	s_add_u32 s8, s8, 0x6000
	s_addc_u32 s9, s9, 0
	global_load_dwordx2 v[180:181], v12, s[8:9]
	s_add_u32 s8, s8, 0x6000
	s_addc_u32 s9, s9, 0
	global_load_dwordx2 v[182:183], v12, s[8:9]
	s_add_u32 s8, s8, 0x6000
	s_addc_u32 s9, s9, 0
	global_load_dwordx2 v[184:185], v12, s[8:9]
	s_add_u32 s8, s8, 0x6000
	s_addc_u32 s9, s9, 0
	global_load_dwordx2 v[186:187], v12, s[8:9]
	s_add_u32 s8, s8, 0x6000
	s_addc_u32 s9, s9, 0
	global_load_dwordx2 v[188:189], v12, s[8:9]
	s_add_u32 s8, s8, 0x6000
	s_addc_u32 s9, s9, 0
	global_load_dwordx2 v[190:191], v12, s[8:9]
	v_mov_b32_e32 v48, 0
	v_mov_b32_e32 v49, 0
	v_mov_b32_e32 v50, 0
	v_mov_b32_e32 v51, 0
	v_mov_b32_e32 v52, 0
	v_mov_b32_e32 v53, 0
	v_mov_b32_e32 v54, 0
	v_mov_b32_e32 v55, 0
	v_mov_b32_e32 v56, 0
	v_mov_b32_e32 v57, 0
	v_mov_b32_e32 v58, 0
	v_mov_b32_e32 v59, 0
	v_mov_b32_e32 v60, 0
	v_mov_b32_e32 v61, 0
	v_mov_b32_e32 v62, 0
	v_mov_b32_e32 v63, 0
	s_waitcnt lgkmcnt(0)
	ds_read_b128 v[200:203], v13 offset:16
	ds_read_b128 v[204:207], v13 offset:4112
	ds_read_b128 v[208:211], v13 offset:8208
	ds_read_b128 v[212:215], v13 offset:12304
	ds_read_b128 v[216:219], v13 offset:16400
	ds_read_b128 v[220:223], v13 offset:20496
	ds_read_b128 v[224:227], v13 offset:24592
	ds_read_b128 v[228:231], v13 offset:28688
	s_waitcnt vmcnt(60)
	v_fmac_f32_e32 v48, v16, v64
	v_fmac_f32_e32 v49, v16, v65
	v_fmac_f32_e32 v50, v20, v64
	v_fmac_f32_e32 v51, v20, v65
	v_fmac_f32_e32 v52, v24, v64
	v_fmac_f32_e32 v53, v24, v65
	v_fmac_f32_e32 v54, v28, v64
	v_fmac_f32_e32 v55, v28, v65
	v_fmac_f32_e32 v56, v32, v64
	v_fmac_f32_e32 v57, v32, v65
	v_fmac_f32_e32 v58, v36, v64
	v_fmac_f32_e32 v59, v36, v65
	v_fmac_f32_e32 v60, v40, v64
	v_fmac_f32_e32 v61, v40, v65
	v_fmac_f32_e32 v62, v44, v64
	v_fmac_f32_e32 v63, v44, v65
	v_fmac_f32_e32 v48, v17, v66
	v_fmac_f32_e32 v49, v17, v67
	v_fmac_f32_e32 v50, v21, v66
	v_fmac_f32_e32 v51, v21, v67
	v_fmac_f32_e32 v52, v25, v66
	v_fmac_f32_e32 v53, v25, v67
	v_fmac_f32_e32 v54, v29, v66
	v_fmac_f32_e32 v55, v29, v67
	v_fmac_f32_e32 v56, v33, v66
	v_fmac_f32_e32 v57, v33, v67
	v_fmac_f32_e32 v58, v37, v66
	v_fmac_f32_e32 v59, v37, v67
	v_fmac_f32_e32 v60, v41, v66
	v_fmac_f32_e32 v61, v41, v67
	v_fmac_f32_e32 v62, v45, v66
	v_fmac_f32_e32 v63, v45, v67
	v_fmac_f32_e32 v48, v18, v68
	v_fmac_f32_e32 v49, v18, v69
	v_fmac_f32_e32 v50, v22, v68
	v_fmac_f32_e32 v51, v22, v69
	v_fmac_f32_e32 v52, v26, v68
	v_fmac_f32_e32 v53, v26, v69
	v_fmac_f32_e32 v54, v30, v68
	v_fmac_f32_e32 v55, v30, v69
	v_fmac_f32_e32 v56, v34, v68
	v_fmac_f32_e32 v57, v34, v69
	v_fmac_f32_e32 v58, v38, v68
	v_fmac_f32_e32 v59, v38, v69
	v_fmac_f32_e32 v60, v42, v68
	v_fmac_f32_e32 v61, v42, v69
	v_fmac_f32_e32 v62, v46, v68
	v_fmac_f32_e32 v63, v46, v69
	v_fmac_f32_e32 v48, v19, v70
	v_fmac_f32_e32 v49, v19, v71
	v_fmac_f32_e32 v50, v23, v70
	v_fmac_f32_e32 v51, v23, v71
	v_fmac_f32_e32 v52, v27, v70
	v_fmac_f32_e32 v53, v27, v71
	v_fmac_f32_e32 v54, v31, v70
	v_fmac_f32_e32 v55, v31, v71
	v_fmac_f32_e32 v56, v35, v70
	v_fmac_f32_e32 v57, v35, v71
	v_fmac_f32_e32 v58, v39, v70
	v_fmac_f32_e32 v59, v39, v71
	v_fmac_f32_e32 v60, v43, v70
	v_fmac_f32_e32 v61, v43, v71
	v_fmac_f32_e32 v62, v47, v70
	v_fmac_f32_e32 v63, v47, v71
	s_waitcnt lgkmcnt(0)
	ds_read_b128 v[16:19], v13 offset:32
	ds_read_b128 v[20:23], v13 offset:4128
	ds_read_b128 v[24:27], v13 offset:8224
	ds_read_b128 v[28:31], v13 offset:12320
	ds_read_b128 v[32:35], v13 offset:16416
	ds_read_b128 v[36:39], v13 offset:20512
	ds_read_b128 v[40:43], v13 offset:24608
	ds_read_b128 v[44:47], v13 offset:28704
	s_waitcnt vmcnt(56)
	v_fmac_f32_e32 v48, v200, v72
	v_fmac_f32_e32 v49, v200, v73
	v_fmac_f32_e32 v50, v204, v72
	v_fmac_f32_e32 v51, v204, v73
	v_fmac_f32_e32 v52, v208, v72
	v_fmac_f32_e32 v53, v208, v73
	v_fmac_f32_e32 v54, v212, v72
	v_fmac_f32_e32 v55, v212, v73
	v_fmac_f32_e32 v56, v216, v72
	v_fmac_f32_e32 v57, v216, v73
	v_fmac_f32_e32 v58, v220, v72
	v_fmac_f32_e32 v59, v220, v73
	v_fmac_f32_e32 v60, v224, v72
	v_fmac_f32_e32 v61, v224, v73
	v_fmac_f32_e32 v62, v228, v72
	v_fmac_f32_e32 v63, v228, v73
	v_fmac_f32_e32 v48, v201, v74
	v_fmac_f32_e32 v49, v201, v75
	v_fmac_f32_e32 v50, v205, v74
	v_fmac_f32_e32 v51, v205, v75
	v_fmac_f32_e32 v52, v209, v74
	v_fmac_f32_e32 v53, v209, v75
	v_fmac_f32_e32 v54, v213, v74
	v_fmac_f32_e32 v55, v213, v75
	v_fmac_f32_e32 v56, v217, v74
	v_fmac_f32_e32 v57, v217, v75
	v_fmac_f32_e32 v58, v221, v74
	v_fmac_f32_e32 v59, v221, v75
	v_fmac_f32_e32 v60, v225, v74
	v_fmac_f32_e32 v61, v225, v75
	v_fmac_f32_e32 v62, v229, v74
	v_fmac_f32_e32 v63, v229, v75
	v_fmac_f32_e32 v48, v202, v76
	v_fmac_f32_e32 v49, v202, v77
	v_fmac_f32_e32 v50, v206, v76
	v_fmac_f32_e32 v51, v206, v77
	v_fmac_f32_e32 v52, v210, v76
	v_fmac_f32_e32 v53, v210, v77
	v_fmac_f32_e32 v54, v214, v76
	v_fmac_f32_e32 v55, v214, v77
	v_fmac_f32_e32 v56, v218, v76
	v_fmac_f32_e32 v57, v218, v77
	v_fmac_f32_e32 v58, v222, v76
	v_fmac_f32_e32 v59, v222, v77
	v_fmac_f32_e32 v60, v226, v76
	v_fmac_f32_e32 v61, v226, v77
	v_fmac_f32_e32 v62, v230, v76
	v_fmac_f32_e32 v63, v230, v77
	v_fmac_f32_e32 v48, v203, v78
	v_fmac_f32_e32 v49, v203, v79
	v_fmac_f32_e32 v50, v207, v78
	v_fmac_f32_e32 v51, v207, v79
	v_fmac_f32_e32 v52, v211, v78
	v_fmac_f32_e32 v53, v211, v79
	v_fmac_f32_e32 v54, v215, v78
	v_fmac_f32_e32 v55, v215, v79
	v_fmac_f32_e32 v56, v219, v78
	v_fmac_f32_e32 v57, v219, v79
	v_fmac_f32_e32 v58, v223, v78
	v_fmac_f32_e32 v59, v223, v79
	v_fmac_f32_e32 v60, v227, v78
	v_fmac_f32_e32 v61, v227, v79
	v_fmac_f32_e32 v62, v231, v78
	v_fmac_f32_e32 v63, v231, v79
	s_waitcnt lgkmcnt(0)
	ds_read_b128 v[200:203], v13 offset:48
	ds_read_b128 v[204:207], v13 offset:4144
	ds_read_b128 v[208:211], v13 offset:8240
	ds_read_b128 v[212:215], v13 offset:12336
	ds_read_b128 v[216:219], v13 offset:16432
	ds_read_b128 v[220:223], v13 offset:20528
	ds_read_b128 v[224:227], v13 offset:24624
	ds_read_b128 v[228:231], v13 offset:28720
	s_waitcnt vmcnt(52)
	v_fmac_f32_e32 v48, v16, v80
	v_fmac_f32_e32 v49, v16, v81
	v_fmac_f32_e32 v50, v20, v80
	v_fmac_f32_e32 v51, v20, v81
	v_fmac_f32_e32 v52, v24, v80
	v_fmac_f32_e32 v53, v24, v81
	v_fmac_f32_e32 v54, v28, v80
	v_fmac_f32_e32 v55, v28, v81
	v_fmac_f32_e32 v56, v32, v80
	v_fmac_f32_e32 v57, v32, v81
	v_fmac_f32_e32 v58, v36, v80
	v_fmac_f32_e32 v59, v36, v81
	v_fmac_f32_e32 v60, v40, v80
	v_fmac_f32_e32 v61, v40, v81
	v_fmac_f32_e32 v62, v44, v80
	v_fmac_f32_e32 v63, v44, v81
	v_fmac_f32_e32 v48, v17, v82
	v_fmac_f32_e32 v49, v17, v83
	v_fmac_f32_e32 v50, v21, v82
	v_fmac_f32_e32 v51, v21, v83
	v_fmac_f32_e32 v52, v25, v82
	v_fmac_f32_e32 v53, v25, v83
	v_fmac_f32_e32 v54, v29, v82
	v_fmac_f32_e32 v55, v29, v83
	v_fmac_f32_e32 v56, v33, v82
	v_fmac_f32_e32 v57, v33, v83
	v_fmac_f32_e32 v58, v37, v82
	v_fmac_f32_e32 v59, v37, v83
	v_fmac_f32_e32 v60, v41, v82
	v_fmac_f32_e32 v61, v41, v83
	v_fmac_f32_e32 v62, v45, v82
	v_fmac_f32_e32 v63, v45, v83
	v_fmac_f32_e32 v48, v18, v84
	v_fmac_f32_e32 v49, v18, v85
	v_fmac_f32_e32 v50, v22, v84
	v_fmac_f32_e32 v51, v22, v85
	v_fmac_f32_e32 v52, v26, v84
	v_fmac_f32_e32 v53, v26, v85
	v_fmac_f32_e32 v54, v30, v84
	v_fmac_f32_e32 v55, v30, v85
	v_fmac_f32_e32 v56, v34, v84
	v_fmac_f32_e32 v57, v34, v85
	v_fmac_f32_e32 v58, v38, v84
	v_fmac_f32_e32 v59, v38, v85
	v_fmac_f32_e32 v60, v42, v84
	v_fmac_f32_e32 v61, v42, v85
	v_fmac_f32_e32 v62, v46, v84
	v_fmac_f32_e32 v63, v46, v85
	v_fmac_f32_e32 v48, v19, v86
	v_fmac_f32_e32 v49, v19, v87
	v_fmac_f32_e32 v50, v23, v86
	v_fmac_f32_e32 v51, v23, v87
	v_fmac_f32_e32 v52, v27, v86
	v_fmac_f32_e32 v53, v27, v87
	v_fmac_f32_e32 v54, v31, v86
	v_fmac_f32_e32 v55, v31, v87
	v_fmac_f32_e32 v56, v35, v86
	v_fmac_f32_e32 v57, v35, v87
	v_fmac_f32_e32 v58, v39, v86
	v_fmac_f32_e32 v59, v39, v87
	v_fmac_f32_e32 v60, v43, v86
	v_fmac_f32_e32 v61, v43, v87
	v_fmac_f32_e32 v62, v47, v86
	v_fmac_f32_e32 v63, v47, v87
	s_waitcnt lgkmcnt(0)
	ds_read_b128 v[16:19], v13 offset:64
	ds_read_b128 v[20:23], v13 offset:4160
	ds_read_b128 v[24:27], v13 offset:8256
	ds_read_b128 v[28:31], v13 offset:12352
	ds_read_b128 v[32:35], v13 offset:16448
	ds_read_b128 v[36:39], v13 offset:20544
	ds_read_b128 v[40:43], v13 offset:24640
	ds_read_b128 v[44:47], v13 offset:28736
	s_waitcnt vmcnt(48)
	v_fmac_f32_e32 v48, v200, v88
	v_fmac_f32_e32 v49, v200, v89
	v_fmac_f32_e32 v50, v204, v88
	v_fmac_f32_e32 v51, v204, v89
	v_fmac_f32_e32 v52, v208, v88
	v_fmac_f32_e32 v53, v208, v89
	v_fmac_f32_e32 v54, v212, v88
	v_fmac_f32_e32 v55, v212, v89
	v_fmac_f32_e32 v56, v216, v88
	v_fmac_f32_e32 v57, v216, v89
	v_fmac_f32_e32 v58, v220, v88
	v_fmac_f32_e32 v59, v220, v89
	v_fmac_f32_e32 v60, v224, v88
	v_fmac_f32_e32 v61, v224, v89
	v_fmac_f32_e32 v62, v228, v88
	v_fmac_f32_e32 v63, v228, v89
	v_fmac_f32_e32 v48, v201, v90
	v_fmac_f32_e32 v49, v201, v91
	v_fmac_f32_e32 v50, v205, v90
	v_fmac_f32_e32 v51, v205, v91
	v_fmac_f32_e32 v52, v209, v90
	v_fmac_f32_e32 v53, v209, v91
	v_fmac_f32_e32 v54, v213, v90
	v_fmac_f32_e32 v55, v213, v91
	v_fmac_f32_e32 v56, v217, v90
	v_fmac_f32_e32 v57, v217, v91
	v_fmac_f32_e32 v58, v221, v90
	v_fmac_f32_e32 v59, v221, v91
	v_fmac_f32_e32 v60, v225, v90
	v_fmac_f32_e32 v61, v225, v91
	v_fmac_f32_e32 v62, v229, v90
	v_fmac_f32_e32 v63, v229, v91
	v_fmac_f32_e32 v48, v202, v92
	v_fmac_f32_e32 v49, v202, v93
	v_fmac_f32_e32 v50, v206, v92
	v_fmac_f32_e32 v51, v206, v93
	v_fmac_f32_e32 v52, v210, v92
	v_fmac_f32_e32 v53, v210, v93
	v_fmac_f32_e32 v54, v214, v92
	v_fmac_f32_e32 v55, v214, v93
	v_fmac_f32_e32 v56, v218, v92
	v_fmac_f32_e32 v57, v218, v93
	v_fmac_f32_e32 v58, v222, v92
	v_fmac_f32_e32 v59, v222, v93
	v_fmac_f32_e32 v60, v226, v92
	v_fmac_f32_e32 v61, v226, v93
	v_fmac_f32_e32 v62, v230, v92
	v_fmac_f32_e32 v63, v230, v93
	v_fmac_f32_e32 v48, v203, v94
	v_fmac_f32_e32 v49, v203, v95
	v_fmac_f32_e32 v50, v207, v94
	v_fmac_f32_e32 v51, v207, v95
	v_fmac_f32_e32 v52, v211, v94
	v_fmac_f32_e32 v53, v211, v95
	v_fmac_f32_e32 v54, v215, v94
	v_fmac_f32_e32 v55, v215, v95
	v_fmac_f32_e32 v56, v219, v94
	v_fmac_f32_e32 v57, v219, v95
	v_fmac_f32_e32 v58, v223, v94
	v_fmac_f32_e32 v59, v223, v95
	v_fmac_f32_e32 v60, v227, v94
	v_fmac_f32_e32 v61, v227, v95
	v_fmac_f32_e32 v62, v231, v94
	v_fmac_f32_e32 v63, v231, v95
	s_waitcnt lgkmcnt(0)
	ds_read_b128 v[200:203], v13 offset:80
	ds_read_b128 v[204:207], v13 offset:4176
	ds_read_b128 v[208:211], v13 offset:8272
	ds_read_b128 v[212:215], v13 offset:12368
	ds_read_b128 v[216:219], v13 offset:16464
	ds_read_b128 v[220:223], v13 offset:20560
	ds_read_b128 v[224:227], v13 offset:24656
	ds_read_b128 v[228:231], v13 offset:28752
	s_waitcnt vmcnt(44)
	v_fmac_f32_e32 v48, v16, v96
	v_fmac_f32_e32 v49, v16, v97
	v_fmac_f32_e32 v50, v20, v96
	v_fmac_f32_e32 v51, v20, v97
	v_fmac_f32_e32 v52, v24, v96
	v_fmac_f32_e32 v53, v24, v97
	v_fmac_f32_e32 v54, v28, v96
	v_fmac_f32_e32 v55, v28, v97
	v_fmac_f32_e32 v56, v32, v96
	v_fmac_f32_e32 v57, v32, v97
	v_fmac_f32_e32 v58, v36, v96
	v_fmac_f32_e32 v59, v36, v97
	v_fmac_f32_e32 v60, v40, v96
	v_fmac_f32_e32 v61, v40, v97
	v_fmac_f32_e32 v62, v44, v96
	v_fmac_f32_e32 v63, v44, v97
	v_fmac_f32_e32 v48, v17, v98
	v_fmac_f32_e32 v49, v17, v99
	v_fmac_f32_e32 v50, v21, v98
	v_fmac_f32_e32 v51, v21, v99
	v_fmac_f32_e32 v52, v25, v98
	v_fmac_f32_e32 v53, v25, v99
	v_fmac_f32_e32 v54, v29, v98
	v_fmac_f32_e32 v55, v29, v99
	v_fmac_f32_e32 v56, v33, v98
	v_fmac_f32_e32 v57, v33, v99
	v_fmac_f32_e32 v58, v37, v98
	v_fmac_f32_e32 v59, v37, v99
	v_fmac_f32_e32 v60, v41, v98
	v_fmac_f32_e32 v61, v41, v99
	v_fmac_f32_e32 v62, v45, v98
	v_fmac_f32_e32 v63, v45, v99
	v_fmac_f32_e32 v48, v18, v100
	v_fmac_f32_e32 v49, v18, v101
	v_fmac_f32_e32 v50, v22, v100
	v_fmac_f32_e32 v51, v22, v101
	v_fmac_f32_e32 v52, v26, v100
	v_fmac_f32_e32 v53, v26, v101
	v_fmac_f32_e32 v54, v30, v100
	v_fmac_f32_e32 v55, v30, v101
	v_fmac_f32_e32 v56, v34, v100
	v_fmac_f32_e32 v57, v34, v101
	v_fmac_f32_e32 v58, v38, v100
	v_fmac_f32_e32 v59, v38, v101
	v_fmac_f32_e32 v60, v42, v100
	v_fmac_f32_e32 v61, v42, v101
	v_fmac_f32_e32 v62, v46, v100
	v_fmac_f32_e32 v63, v46, v101
	v_fmac_f32_e32 v48, v19, v102
	v_fmac_f32_e32 v49, v19, v103
	v_fmac_f32_e32 v50, v23, v102
	v_fmac_f32_e32 v51, v23, v103
	v_fmac_f32_e32 v52, v27, v102
	v_fmac_f32_e32 v53, v27, v103
	v_fmac_f32_e32 v54, v31, v102
	v_fmac_f32_e32 v55, v31, v103
	v_fmac_f32_e32 v56, v35, v102
	v_fmac_f32_e32 v57, v35, v103
	v_fmac_f32_e32 v58, v39, v102
	v_fmac_f32_e32 v59, v39, v103
	v_fmac_f32_e32 v60, v43, v102
	v_fmac_f32_e32 v61, v43, v103
	v_fmac_f32_e32 v62, v47, v102
	v_fmac_f32_e32 v63, v47, v103
	s_waitcnt lgkmcnt(0)
	ds_read_b128 v[16:19], v13 offset:96
	ds_read_b128 v[20:23], v13 offset:4192
	ds_read_b128 v[24:27], v13 offset:8288
	ds_read_b128 v[28:31], v13 offset:12384
	ds_read_b128 v[32:35], v13 offset:16480
	ds_read_b128 v[36:39], v13 offset:20576
	ds_read_b128 v[40:43], v13 offset:24672
	ds_read_b128 v[44:47], v13 offset:28768
	s_waitcnt vmcnt(40)
	v_fmac_f32_e32 v48, v200, v104
	v_fmac_f32_e32 v49, v200, v105
	v_fmac_f32_e32 v50, v204, v104
	v_fmac_f32_e32 v51, v204, v105
	v_fmac_f32_e32 v52, v208, v104
	v_fmac_f32_e32 v53, v208, v105
	v_fmac_f32_e32 v54, v212, v104
	v_fmac_f32_e32 v55, v212, v105
	v_fmac_f32_e32 v56, v216, v104
	v_fmac_f32_e32 v57, v216, v105
	v_fmac_f32_e32 v58, v220, v104
	v_fmac_f32_e32 v59, v220, v105
	v_fmac_f32_e32 v60, v224, v104
	v_fmac_f32_e32 v61, v224, v105
	v_fmac_f32_e32 v62, v228, v104
	v_fmac_f32_e32 v63, v228, v105
	v_fmac_f32_e32 v48, v201, v106
	v_fmac_f32_e32 v49, v201, v107
	v_fmac_f32_e32 v50, v205, v106
	v_fmac_f32_e32 v51, v205, v107
	v_fmac_f32_e32 v52, v209, v106
	v_fmac_f32_e32 v53, v209, v107
	v_fmac_f32_e32 v54, v213, v106
	v_fmac_f32_e32 v55, v213, v107
	v_fmac_f32_e32 v56, v217, v106
	v_fmac_f32_e32 v57, v217, v107
	v_fmac_f32_e32 v58, v221, v106
	v_fmac_f32_e32 v59, v221, v107
	v_fmac_f32_e32 v60, v225, v106
	v_fmac_f32_e32 v61, v225, v107
	v_fmac_f32_e32 v62, v229, v106
	v_fmac_f32_e32 v63, v229, v107
	v_fmac_f32_e32 v48, v202, v108
	v_fmac_f32_e32 v49, v202, v109
	v_fmac_f32_e32 v50, v206, v108
	v_fmac_f32_e32 v51, v206, v109
	v_fmac_f32_e32 v52, v210, v108
	v_fmac_f32_e32 v53, v210, v109
	v_fmac_f32_e32 v54, v214, v108
	v_fmac_f32_e32 v55, v214, v109
	v_fmac_f32_e32 v56, v218, v108
	v_fmac_f32_e32 v57, v218, v109
	v_fmac_f32_e32 v58, v222, v108
	v_fmac_f32_e32 v59, v222, v109
	v_fmac_f32_e32 v60, v226, v108
	v_fmac_f32_e32 v61, v226, v109
	v_fmac_f32_e32 v62, v230, v108
	v_fmac_f32_e32 v63, v230, v109
	v_fmac_f32_e32 v48, v203, v110
	v_fmac_f32_e32 v49, v203, v111
	v_fmac_f32_e32 v50, v207, v110
	v_fmac_f32_e32 v51, v207, v111
	v_fmac_f32_e32 v52, v211, v110
	v_fmac_f32_e32 v53, v211, v111
	v_fmac_f32_e32 v54, v215, v110
	v_fmac_f32_e32 v55, v215, v111
	v_fmac_f32_e32 v56, v219, v110
	v_fmac_f32_e32 v57, v219, v111
	v_fmac_f32_e32 v58, v223, v110
	v_fmac_f32_e32 v59, v223, v111
	v_fmac_f32_e32 v60, v227, v110
	v_fmac_f32_e32 v61, v227, v111
	v_fmac_f32_e32 v62, v231, v110
	v_fmac_f32_e32 v63, v231, v111
	s_waitcnt lgkmcnt(0)
	ds_read_b128 v[200:203], v13 offset:112
	ds_read_b128 v[204:207], v13 offset:4208
	ds_read_b128 v[208:211], v13 offset:8304
	ds_read_b128 v[212:215], v13 offset:12400
	ds_read_b128 v[216:219], v13 offset:16496
	ds_read_b128 v[220:223], v13 offset:20592
	ds_read_b128 v[224:227], v13 offset:24688
	ds_read_b128 v[228:231], v13 offset:28784
	s_waitcnt vmcnt(36)
	v_fmac_f32_e32 v48, v16, v112
	v_fmac_f32_e32 v49, v16, v113
	v_fmac_f32_e32 v50, v20, v112
	v_fmac_f32_e32 v51, v20, v113
	v_fmac_f32_e32 v52, v24, v112
	v_fmac_f32_e32 v53, v24, v113
	v_fmac_f32_e32 v54, v28, v112
	v_fmac_f32_e32 v55, v28, v113
	v_fmac_f32_e32 v56, v32, v112
	v_fmac_f32_e32 v57, v32, v113
	v_fmac_f32_e32 v58, v36, v112
	v_fmac_f32_e32 v59, v36, v113
	v_fmac_f32_e32 v60, v40, v112
	v_fmac_f32_e32 v61, v40, v113
	v_fmac_f32_e32 v62, v44, v112
	v_fmac_f32_e32 v63, v44, v113
	v_fmac_f32_e32 v48, v17, v114
	v_fmac_f32_e32 v49, v17, v115
	v_fmac_f32_e32 v50, v21, v114
	v_fmac_f32_e32 v51, v21, v115
	v_fmac_f32_e32 v52, v25, v114
	v_fmac_f32_e32 v53, v25, v115
	v_fmac_f32_e32 v54, v29, v114
	v_fmac_f32_e32 v55, v29, v115
	v_fmac_f32_e32 v56, v33, v114
	v_fmac_f32_e32 v57, v33, v115
	v_fmac_f32_e32 v58, v37, v114
	v_fmac_f32_e32 v59, v37, v115
	v_fmac_f32_e32 v60, v41, v114
	v_fmac_f32_e32 v61, v41, v115
	v_fmac_f32_e32 v62, v45, v114
	v_fmac_f32_e32 v63, v45, v115
	v_fmac_f32_e32 v48, v18, v116
	v_fmac_f32_e32 v49, v18, v117
	v_fmac_f32_e32 v50, v22, v116
	v_fmac_f32_e32 v51, v22, v117
	v_fmac_f32_e32 v52, v26, v116
	v_fmac_f32_e32 v53, v26, v117
	v_fmac_f32_e32 v54, v30, v116
	v_fmac_f32_e32 v55, v30, v117
	v_fmac_f32_e32 v56, v34, v116
	v_fmac_f32_e32 v57, v34, v117
	v_fmac_f32_e32 v58, v38, v116
	v_fmac_f32_e32 v59, v38, v117
	v_fmac_f32_e32 v60, v42, v116
	v_fmac_f32_e32 v61, v42, v117
	v_fmac_f32_e32 v62, v46, v116
	v_fmac_f32_e32 v63, v46, v117
	v_fmac_f32_e32 v48, v19, v118
	v_fmac_f32_e32 v49, v19, v119
	v_fmac_f32_e32 v50, v23, v118
	v_fmac_f32_e32 v51, v23, v119
	v_fmac_f32_e32 v52, v27, v118
	v_fmac_f32_e32 v53, v27, v119
	v_fmac_f32_e32 v54, v31, v118
	v_fmac_f32_e32 v55, v31, v119
	v_fmac_f32_e32 v56, v35, v118
	v_fmac_f32_e32 v57, v35, v119
	v_fmac_f32_e32 v58, v39, v118
	v_fmac_f32_e32 v59, v39, v119
	v_fmac_f32_e32 v60, v43, v118
	v_fmac_f32_e32 v61, v43, v119
	v_fmac_f32_e32 v62, v47, v118
	v_fmac_f32_e32 v63, v47, v119
	s_waitcnt lgkmcnt(0)
	ds_read_b128 v[16:19], v13 offset:128
	ds_read_b128 v[20:23], v13 offset:4224
	ds_read_b128 v[24:27], v13 offset:8320
	ds_read_b128 v[28:31], v13 offset:12416
	ds_read_b128 v[32:35], v13 offset:16512
	ds_read_b128 v[36:39], v13 offset:20608
	ds_read_b128 v[40:43], v13 offset:24704
	ds_read_b128 v[44:47], v13 offset:28800
	s_waitcnt vmcnt(32)
	v_fmac_f32_e32 v48, v200, v120
	v_fmac_f32_e32 v49, v200, v121
	v_fmac_f32_e32 v50, v204, v120
	v_fmac_f32_e32 v51, v204, v121
	v_fmac_f32_e32 v52, v208, v120
	v_fmac_f32_e32 v53, v208, v121
	v_fmac_f32_e32 v54, v212, v120
	v_fmac_f32_e32 v55, v212, v121
	v_fmac_f32_e32 v56, v216, v120
	v_fmac_f32_e32 v57, v216, v121
	v_fmac_f32_e32 v58, v220, v120
	v_fmac_f32_e32 v59, v220, v121
	v_fmac_f32_e32 v60, v224, v120
	v_fmac_f32_e32 v61, v224, v121
	v_fmac_f32_e32 v62, v228, v120
	v_fmac_f32_e32 v63, v228, v121
	v_fmac_f32_e32 v48, v201, v122
	v_fmac_f32_e32 v49, v201, v123
	v_fmac_f32_e32 v50, v205, v122
	v_fmac_f32_e32 v51, v205, v123
	v_fmac_f32_e32 v52, v209, v122
	v_fmac_f32_e32 v53, v209, v123
	v_fmac_f32_e32 v54, v213, v122
	v_fmac_f32_e32 v55, v213, v123
	v_fmac_f32_e32 v56, v217, v122
	v_fmac_f32_e32 v57, v217, v123
	v_fmac_f32_e32 v58, v221, v122
	v_fmac_f32_e32 v59, v221, v123
	v_fmac_f32_e32 v60, v225, v122
	v_fmac_f32_e32 v61, v225, v123
	v_fmac_f32_e32 v62, v229, v122
	v_fmac_f32_e32 v63, v229, v123
	v_fmac_f32_e32 v48, v202, v124
	v_fmac_f32_e32 v49, v202, v125
	v_fmac_f32_e32 v50, v206, v124
	v_fmac_f32_e32 v51, v206, v125
	v_fmac_f32_e32 v52, v210, v124
	v_fmac_f32_e32 v53, v210, v125
	v_fmac_f32_e32 v54, v214, v124
	v_fmac_f32_e32 v55, v214, v125
	v_fmac_f32_e32 v56, v218, v124
	v_fmac_f32_e32 v57, v218, v125
	v_fmac_f32_e32 v58, v222, v124
	v_fmac_f32_e32 v59, v222, v125
	v_fmac_f32_e32 v60, v226, v124
	v_fmac_f32_e32 v61, v226, v125
	v_fmac_f32_e32 v62, v230, v124
	v_fmac_f32_e32 v63, v230, v125
	v_fmac_f32_e32 v48, v203, v126
	v_fmac_f32_e32 v49, v203, v127
	v_fmac_f32_e32 v50, v207, v126
	v_fmac_f32_e32 v51, v207, v127
	v_fmac_f32_e32 v52, v211, v126
	v_fmac_f32_e32 v53, v211, v127
	v_fmac_f32_e32 v54, v215, v126
	v_fmac_f32_e32 v55, v215, v127
	v_fmac_f32_e32 v56, v219, v126
	v_fmac_f32_e32 v57, v219, v127
	v_fmac_f32_e32 v58, v223, v126
	v_fmac_f32_e32 v59, v223, v127
	v_fmac_f32_e32 v60, v227, v126
	v_fmac_f32_e32 v61, v227, v127
	v_fmac_f32_e32 v62, v231, v126
	v_fmac_f32_e32 v63, v231, v127
	s_waitcnt lgkmcnt(0)
	ds_read_b128 v[200:203], v13 offset:144
	ds_read_b128 v[204:207], v13 offset:4240
	ds_read_b128 v[208:211], v13 offset:8336
	ds_read_b128 v[212:215], v13 offset:12432
	ds_read_b128 v[216:219], v13 offset:16528
	ds_read_b128 v[220:223], v13 offset:20624
	ds_read_b128 v[224:227], v13 offset:24720
	ds_read_b128 v[228:231], v13 offset:28816
	s_waitcnt vmcnt(28)
	v_fmac_f32_e32 v48, v16, v128
	v_fmac_f32_e32 v49, v16, v129
	v_fmac_f32_e32 v50, v20, v128
	v_fmac_f32_e32 v51, v20, v129
	v_fmac_f32_e32 v52, v24, v128
	v_fmac_f32_e32 v53, v24, v129
	v_fmac_f32_e32 v54, v28, v128
	v_fmac_f32_e32 v55, v28, v129
	v_fmac_f32_e32 v56, v32, v128
	v_fmac_f32_e32 v57, v32, v129
	v_fmac_f32_e32 v58, v36, v128
	v_fmac_f32_e32 v59, v36, v129
	v_fmac_f32_e32 v60, v40, v128
	v_fmac_f32_e32 v61, v40, v129
	v_fmac_f32_e32 v62, v44, v128
	v_fmac_f32_e32 v63, v44, v129
	v_fmac_f32_e32 v48, v17, v130
	v_fmac_f32_e32 v49, v17, v131
	v_fmac_f32_e32 v50, v21, v130
	v_fmac_f32_e32 v51, v21, v131
	v_fmac_f32_e32 v52, v25, v130
	v_fmac_f32_e32 v53, v25, v131
	v_fmac_f32_e32 v54, v29, v130
	v_fmac_f32_e32 v55, v29, v131
	v_fmac_f32_e32 v56, v33, v130
	v_fmac_f32_e32 v57, v33, v131
	v_fmac_f32_e32 v58, v37, v130
	v_fmac_f32_e32 v59, v37, v131
	v_fmac_f32_e32 v60, v41, v130
	v_fmac_f32_e32 v61, v41, v131
	v_fmac_f32_e32 v62, v45, v130
	v_fmac_f32_e32 v63, v45, v131
	v_fmac_f32_e32 v48, v18, v132
	v_fmac_f32_e32 v49, v18, v133
	v_fmac_f32_e32 v50, v22, v132
	v_fmac_f32_e32 v51, v22, v133
	v_fmac_f32_e32 v52, v26, v132
	v_fmac_f32_e32 v53, v26, v133
	v_fmac_f32_e32 v54, v30, v132
	v_fmac_f32_e32 v55, v30, v133
	v_fmac_f32_e32 v56, v34, v132
	v_fmac_f32_e32 v57, v34, v133
	v_fmac_f32_e32 v58, v38, v132
	v_fmac_f32_e32 v59, v38, v133
	v_fmac_f32_e32 v60, v42, v132
	v_fmac_f32_e32 v61, v42, v133
	v_fmac_f32_e32 v62, v46, v132
	v_fmac_f32_e32 v63, v46, v133
	v_fmac_f32_e32 v48, v19, v134
	v_fmac_f32_e32 v49, v19, v135
	v_fmac_f32_e32 v50, v23, v134
	v_fmac_f32_e32 v51, v23, v135
	v_fmac_f32_e32 v52, v27, v134
	v_fmac_f32_e32 v53, v27, v135
	v_fmac_f32_e32 v54, v31, v134
	v_fmac_f32_e32 v55, v31, v135
	v_fmac_f32_e32 v56, v35, v134
	v_fmac_f32_e32 v57, v35, v135
	v_fmac_f32_e32 v58, v39, v134
	v_fmac_f32_e32 v59, v39, v135
	v_fmac_f32_e32 v60, v43, v134
	v_fmac_f32_e32 v61, v43, v135
	v_fmac_f32_e32 v62, v47, v134
	v_fmac_f32_e32 v63, v47, v135
	s_waitcnt lgkmcnt(0)
	ds_read_b128 v[16:19], v13 offset:160
	ds_read_b128 v[20:23], v13 offset:4256
	ds_read_b128 v[24:27], v13 offset:8352
	ds_read_b128 v[28:31], v13 offset:12448
	ds_read_b128 v[32:35], v13 offset:16544
	ds_read_b128 v[36:39], v13 offset:20640
	ds_read_b128 v[40:43], v13 offset:24736
	ds_read_b128 v[44:47], v13 offset:28832
	s_waitcnt vmcnt(24)
	v_fmac_f32_e32 v48, v200, v136
	v_fmac_f32_e32 v49, v200, v137
	v_fmac_f32_e32 v50, v204, v136
	v_fmac_f32_e32 v51, v204, v137
	v_fmac_f32_e32 v52, v208, v136
	v_fmac_f32_e32 v53, v208, v137
	v_fmac_f32_e32 v54, v212, v136
	v_fmac_f32_e32 v55, v212, v137
	v_fmac_f32_e32 v56, v216, v136
	v_fmac_f32_e32 v57, v216, v137
	v_fmac_f32_e32 v58, v220, v136
	v_fmac_f32_e32 v59, v220, v137
	v_fmac_f32_e32 v60, v224, v136
	v_fmac_f32_e32 v61, v224, v137
	v_fmac_f32_e32 v62, v228, v136
	v_fmac_f32_e32 v63, v228, v137
	v_fmac_f32_e32 v48, v201, v138
	v_fmac_f32_e32 v49, v201, v139
	v_fmac_f32_e32 v50, v205, v138
	v_fmac_f32_e32 v51, v205, v139
	v_fmac_f32_e32 v52, v209, v138
	v_fmac_f32_e32 v53, v209, v139
	v_fmac_f32_e32 v54, v213, v138
	v_fmac_f32_e32 v55, v213, v139
	v_fmac_f32_e32 v56, v217, v138
	v_fmac_f32_e32 v57, v217, v139
	v_fmac_f32_e32 v58, v221, v138
	v_fmac_f32_e32 v59, v221, v139
	v_fmac_f32_e32 v60, v225, v138
	v_fmac_f32_e32 v61, v225, v139
	v_fmac_f32_e32 v62, v229, v138
	v_fmac_f32_e32 v63, v229, v139
	v_fmac_f32_e32 v48, v202, v140
	v_fmac_f32_e32 v49, v202, v141
	v_fmac_f32_e32 v50, v206, v140
	v_fmac_f32_e32 v51, v206, v141
	v_fmac_f32_e32 v52, v210, v140
	v_fmac_f32_e32 v53, v210, v141
	v_fmac_f32_e32 v54, v214, v140
	v_fmac_f32_e32 v55, v214, v141
	v_fmac_f32_e32 v56, v218, v140
	v_fmac_f32_e32 v57, v218, v141
	v_fmac_f32_e32 v58, v222, v140
	v_fmac_f32_e32 v59, v222, v141
	v_fmac_f32_e32 v60, v226, v140
	v_fmac_f32_e32 v61, v226, v141
	v_fmac_f32_e32 v62, v230, v140
	v_fmac_f32_e32 v63, v230, v141
	v_fmac_f32_e32 v48, v203, v142
	v_fmac_f32_e32 v49, v203, v143
	v_fmac_f32_e32 v50, v207, v142
	v_fmac_f32_e32 v51, v207, v143
	v_fmac_f32_e32 v52, v211, v142
	v_fmac_f32_e32 v53, v211, v143
	v_fmac_f32_e32 v54, v215, v142
	v_fmac_f32_e32 v55, v215, v143
	v_fmac_f32_e32 v56, v219, v142
	v_fmac_f32_e32 v57, v219, v143
	v_fmac_f32_e32 v58, v223, v142
	v_fmac_f32_e32 v59, v223, v143
	v_fmac_f32_e32 v60, v227, v142
	v_fmac_f32_e32 v61, v227, v143
	v_fmac_f32_e32 v62, v231, v142
	v_fmac_f32_e32 v63, v231, v143
	s_waitcnt lgkmcnt(0)
	ds_read_b128 v[200:203], v13 offset:176
	ds_read_b128 v[204:207], v13 offset:4272
	ds_read_b128 v[208:211], v13 offset:8368
	ds_read_b128 v[212:215], v13 offset:12464
	ds_read_b128 v[216:219], v13 offset:16560
	ds_read_b128 v[220:223], v13 offset:20656
	ds_read_b128 v[224:227], v13 offset:24752
	ds_read_b128 v[228:231], v13 offset:28848
	s_waitcnt vmcnt(20)
	v_fmac_f32_e32 v48, v16, v144
	v_fmac_f32_e32 v49, v16, v145
	v_fmac_f32_e32 v50, v20, v144
	v_fmac_f32_e32 v51, v20, v145
	v_fmac_f32_e32 v52, v24, v144
	v_fmac_f32_e32 v53, v24, v145
	v_fmac_f32_e32 v54, v28, v144
	v_fmac_f32_e32 v55, v28, v145
	v_fmac_f32_e32 v56, v32, v144
	v_fmac_f32_e32 v57, v32, v145
	v_fmac_f32_e32 v58, v36, v144
	v_fmac_f32_e32 v59, v36, v145
	v_fmac_f32_e32 v60, v40, v144
	v_fmac_f32_e32 v61, v40, v145
	v_fmac_f32_e32 v62, v44, v144
	v_fmac_f32_e32 v63, v44, v145
	v_fmac_f32_e32 v48, v17, v146
	v_fmac_f32_e32 v49, v17, v147
	v_fmac_f32_e32 v50, v21, v146
	v_fmac_f32_e32 v51, v21, v147
	v_fmac_f32_e32 v52, v25, v146
	v_fmac_f32_e32 v53, v25, v147
	v_fmac_f32_e32 v54, v29, v146
	v_fmac_f32_e32 v55, v29, v147
	v_fmac_f32_e32 v56, v33, v146
	v_fmac_f32_e32 v57, v33, v147
	v_fmac_f32_e32 v58, v37, v146
	v_fmac_f32_e32 v59, v37, v147
	v_fmac_f32_e32 v60, v41, v146
	v_fmac_f32_e32 v61, v41, v147
	v_fmac_f32_e32 v62, v45, v146
	v_fmac_f32_e32 v63, v45, v147
	v_fmac_f32_e32 v48, v18, v148
	v_fmac_f32_e32 v49, v18, v149
	v_fmac_f32_e32 v50, v22, v148
	v_fmac_f32_e32 v51, v22, v149
	v_fmac_f32_e32 v52, v26, v148
	v_fmac_f32_e32 v53, v26, v149
	v_fmac_f32_e32 v54, v30, v148
	v_fmac_f32_e32 v55, v30, v149
	v_fmac_f32_e32 v56, v34, v148
	v_fmac_f32_e32 v57, v34, v149
	v_fmac_f32_e32 v58, v38, v148
	v_fmac_f32_e32 v59, v38, v149
	v_fmac_f32_e32 v60, v42, v148
	v_fmac_f32_e32 v61, v42, v149
	v_fmac_f32_e32 v62, v46, v148
	v_fmac_f32_e32 v63, v46, v149
	v_fmac_f32_e32 v48, v19, v150
	v_fmac_f32_e32 v49, v19, v151
	v_fmac_f32_e32 v50, v23, v150
	v_fmac_f32_e32 v51, v23, v151
	v_fmac_f32_e32 v52, v27, v150
	v_fmac_f32_e32 v53, v27, v151
	v_fmac_f32_e32 v54, v31, v150
	v_fmac_f32_e32 v55, v31, v151
	v_fmac_f32_e32 v56, v35, v150
	v_fmac_f32_e32 v57, v35, v151
	v_fmac_f32_e32 v58, v39, v150
	v_fmac_f32_e32 v59, v39, v151
	v_fmac_f32_e32 v60, v43, v150
	v_fmac_f32_e32 v61, v43, v151
	v_fmac_f32_e32 v62, v47, v150
	v_fmac_f32_e32 v63, v47, v151
	s_waitcnt lgkmcnt(0)
	ds_read_b128 v[16:19], v13 offset:192
	ds_read_b128 v[20:23], v13 offset:4288
	ds_read_b128 v[24:27], v13 offset:8384
	ds_read_b128 v[28:31], v13 offset:12480
	ds_read_b128 v[32:35], v13 offset:16576
	ds_read_b128 v[36:39], v13 offset:20672
	ds_read_b128 v[40:43], v13 offset:24768
	ds_read_b128 v[44:47], v13 offset:28864
	s_waitcnt vmcnt(16)
	v_fmac_f32_e32 v48, v200, v152
	v_fmac_f32_e32 v49, v200, v153
	v_fmac_f32_e32 v50, v204, v152
	v_fmac_f32_e32 v51, v204, v153
	v_fmac_f32_e32 v52, v208, v152
	v_fmac_f32_e32 v53, v208, v153
	v_fmac_f32_e32 v54, v212, v152
	v_fmac_f32_e32 v55, v212, v153
	v_fmac_f32_e32 v56, v216, v152
	v_fmac_f32_e32 v57, v216, v153
	v_fmac_f32_e32 v58, v220, v152
	v_fmac_f32_e32 v59, v220, v153
	v_fmac_f32_e32 v60, v224, v152
	v_fmac_f32_e32 v61, v224, v153
	v_fmac_f32_e32 v62, v228, v152
	v_fmac_f32_e32 v63, v228, v153
	v_fmac_f32_e32 v48, v201, v154
	v_fmac_f32_e32 v49, v201, v155
	v_fmac_f32_e32 v50, v205, v154
	v_fmac_f32_e32 v51, v205, v155
	v_fmac_f32_e32 v52, v209, v154
	v_fmac_f32_e32 v53, v209, v155
	v_fmac_f32_e32 v54, v213, v154
	v_fmac_f32_e32 v55, v213, v155
	v_fmac_f32_e32 v56, v217, v154
	v_fmac_f32_e32 v57, v217, v155
	v_fmac_f32_e32 v58, v221, v154
	v_fmac_f32_e32 v59, v221, v155
	v_fmac_f32_e32 v60, v225, v154
	v_fmac_f32_e32 v61, v225, v155
	v_fmac_f32_e32 v62, v229, v154
	v_fmac_f32_e32 v63, v229, v155
	v_fmac_f32_e32 v48, v202, v156
	v_fmac_f32_e32 v49, v202, v157
	v_fmac_f32_e32 v50, v206, v156
	v_fmac_f32_e32 v51, v206, v157
	v_fmac_f32_e32 v52, v210, v156
	v_fmac_f32_e32 v53, v210, v157
	v_fmac_f32_e32 v54, v214, v156
	v_fmac_f32_e32 v55, v214, v157
	v_fmac_f32_e32 v56, v218, v156
	v_fmac_f32_e32 v57, v218, v157
	v_fmac_f32_e32 v58, v222, v156
	v_fmac_f32_e32 v59, v222, v157
	v_fmac_f32_e32 v60, v226, v156
	v_fmac_f32_e32 v61, v226, v157
	v_fmac_f32_e32 v62, v230, v156
	v_fmac_f32_e32 v63, v230, v157
	v_fmac_f32_e32 v48, v203, v158
	v_fmac_f32_e32 v49, v203, v159
	v_fmac_f32_e32 v50, v207, v158
	v_fmac_f32_e32 v51, v207, v159
	v_fmac_f32_e32 v52, v211, v158
	v_fmac_f32_e32 v53, v211, v159
	v_fmac_f32_e32 v54, v215, v158
	v_fmac_f32_e32 v55, v215, v159
	v_fmac_f32_e32 v56, v219, v158
	v_fmac_f32_e32 v57, v219, v159
	v_fmac_f32_e32 v58, v223, v158
	v_fmac_f32_e32 v59, v223, v159
	v_fmac_f32_e32 v60, v227, v158
	v_fmac_f32_e32 v61, v227, v159
	v_fmac_f32_e32 v62, v231, v158
	v_fmac_f32_e32 v63, v231, v159
	s_waitcnt lgkmcnt(0)
	ds_read_b128 v[200:203], v13 offset:208
	ds_read_b128 v[204:207], v13 offset:4304
	ds_read_b128 v[208:211], v13 offset:8400
	ds_read_b128 v[212:215], v13 offset:12496
	ds_read_b128 v[216:219], v13 offset:16592
	ds_read_b128 v[220:223], v13 offset:20688
	ds_read_b128 v[224:227], v13 offset:24784
	ds_read_b128 v[228:231], v13 offset:28880
	s_waitcnt vmcnt(12)
	v_fmac_f32_e32 v48, v16, v160
	v_fmac_f32_e32 v49, v16, v161
	v_fmac_f32_e32 v50, v20, v160
	v_fmac_f32_e32 v51, v20, v161
	v_fmac_f32_e32 v52, v24, v160
	v_fmac_f32_e32 v53, v24, v161
	v_fmac_f32_e32 v54, v28, v160
	v_fmac_f32_e32 v55, v28, v161
	v_fmac_f32_e32 v56, v32, v160
	v_fmac_f32_e32 v57, v32, v161
	v_fmac_f32_e32 v58, v36, v160
	v_fmac_f32_e32 v59, v36, v161
	v_fmac_f32_e32 v60, v40, v160
	v_fmac_f32_e32 v61, v40, v161
	v_fmac_f32_e32 v62, v44, v160
	v_fmac_f32_e32 v63, v44, v161
	v_fmac_f32_e32 v48, v17, v162
	v_fmac_f32_e32 v49, v17, v163
	v_fmac_f32_e32 v50, v21, v162
	v_fmac_f32_e32 v51, v21, v163
	v_fmac_f32_e32 v52, v25, v162
	v_fmac_f32_e32 v53, v25, v163
	v_fmac_f32_e32 v54, v29, v162
	v_fmac_f32_e32 v55, v29, v163
	v_fmac_f32_e32 v56, v33, v162
	v_fmac_f32_e32 v57, v33, v163
	v_fmac_f32_e32 v58, v37, v162
	v_fmac_f32_e32 v59, v37, v163
	v_fmac_f32_e32 v60, v41, v162
	v_fmac_f32_e32 v61, v41, v163
	v_fmac_f32_e32 v62, v45, v162
	v_fmac_f32_e32 v63, v45, v163
	v_fmac_f32_e32 v48, v18, v164
	v_fmac_f32_e32 v49, v18, v165
	v_fmac_f32_e32 v50, v22, v164
	v_fmac_f32_e32 v51, v22, v165
	v_fmac_f32_e32 v52, v26, v164
	v_fmac_f32_e32 v53, v26, v165
	v_fmac_f32_e32 v54, v30, v164
	v_fmac_f32_e32 v55, v30, v165
	v_fmac_f32_e32 v56, v34, v164
	v_fmac_f32_e32 v57, v34, v165
	v_fmac_f32_e32 v58, v38, v164
	v_fmac_f32_e32 v59, v38, v165
	v_fmac_f32_e32 v60, v42, v164
	v_fmac_f32_e32 v61, v42, v165
	v_fmac_f32_e32 v62, v46, v164
	v_fmac_f32_e32 v63, v46, v165
	v_fmac_f32_e32 v48, v19, v166
	v_fmac_f32_e32 v49, v19, v167
	v_fmac_f32_e32 v50, v23, v166
	v_fmac_f32_e32 v51, v23, v167
	v_fmac_f32_e32 v52, v27, v166
	v_fmac_f32_e32 v53, v27, v167
	v_fmac_f32_e32 v54, v31, v166
	v_fmac_f32_e32 v55, v31, v167
	v_fmac_f32_e32 v56, v35, v166
	v_fmac_f32_e32 v57, v35, v167
	v_fmac_f32_e32 v58, v39, v166
	v_fmac_f32_e32 v59, v39, v167
	v_fmac_f32_e32 v60, v43, v166
	v_fmac_f32_e32 v61, v43, v167
	v_fmac_f32_e32 v62, v47, v166
	v_fmac_f32_e32 v63, v47, v167
	s_waitcnt lgkmcnt(0)
	ds_read_b128 v[16:19], v13 offset:224
	ds_read_b128 v[20:23], v13 offset:4320
	ds_read_b128 v[24:27], v13 offset:8416
	ds_read_b128 v[28:31], v13 offset:12512
	ds_read_b128 v[32:35], v13 offset:16608
	ds_read_b128 v[36:39], v13 offset:20704
	ds_read_b128 v[40:43], v13 offset:24800
	ds_read_b128 v[44:47], v13 offset:28896
	s_waitcnt vmcnt(8)
	v_fmac_f32_e32 v48, v200, v168
	v_fmac_f32_e32 v49, v200, v169
	v_fmac_f32_e32 v50, v204, v168
	v_fmac_f32_e32 v51, v204, v169
	v_fmac_f32_e32 v52, v208, v168
	v_fmac_f32_e32 v53, v208, v169
	v_fmac_f32_e32 v54, v212, v168
	v_fmac_f32_e32 v55, v212, v169
	v_fmac_f32_e32 v56, v216, v168
	v_fmac_f32_e32 v57, v216, v169
	v_fmac_f32_e32 v58, v220, v168
	v_fmac_f32_e32 v59, v220, v169
	v_fmac_f32_e32 v60, v224, v168
	v_fmac_f32_e32 v61, v224, v169
	v_fmac_f32_e32 v62, v228, v168
	v_fmac_f32_e32 v63, v228, v169
	v_fmac_f32_e32 v48, v201, v170
	v_fmac_f32_e32 v49, v201, v171
	v_fmac_f32_e32 v50, v205, v170
	v_fmac_f32_e32 v51, v205, v171
	v_fmac_f32_e32 v52, v209, v170
	v_fmac_f32_e32 v53, v209, v171
	v_fmac_f32_e32 v54, v213, v170
	v_fmac_f32_e32 v55, v213, v171
	v_fmac_f32_e32 v56, v217, v170
	v_fmac_f32_e32 v57, v217, v171
	v_fmac_f32_e32 v58, v221, v170
	v_fmac_f32_e32 v59, v221, v171
	v_fmac_f32_e32 v60, v225, v170
	v_fmac_f32_e32 v61, v225, v171
	v_fmac_f32_e32 v62, v229, v170
	v_fmac_f32_e32 v63, v229, v171
	v_fmac_f32_e32 v48, v202, v172
	v_fmac_f32_e32 v49, v202, v173
	v_fmac_f32_e32 v50, v206, v172
	v_fmac_f32_e32 v51, v206, v173
	v_fmac_f32_e32 v52, v210, v172
	v_fmac_f32_e32 v53, v210, v173
	v_fmac_f32_e32 v54, v214, v172
	v_fmac_f32_e32 v55, v214, v173
	v_fmac_f32_e32 v56, v218, v172
	v_fmac_f32_e32 v57, v218, v173
	v_fmac_f32_e32 v58, v222, v172
	v_fmac_f32_e32 v59, v222, v173
	v_fmac_f32_e32 v60, v226, v172
	v_fmac_f32_e32 v61, v226, v173
	v_fmac_f32_e32 v62, v230, v172
	v_fmac_f32_e32 v63, v230, v173
	v_fmac_f32_e32 v48, v203, v174
	v_fmac_f32_e32 v49, v203, v175
	v_fmac_f32_e32 v50, v207, v174
	v_fmac_f32_e32 v51, v207, v175
	v_fmac_f32_e32 v52, v211, v174
	v_fmac_f32_e32 v53, v211, v175
	v_fmac_f32_e32 v54, v215, v174
	v_fmac_f32_e32 v55, v215, v175
	v_fmac_f32_e32 v56, v219, v174
	v_fmac_f32_e32 v57, v219, v175
	v_fmac_f32_e32 v58, v223, v174
	v_fmac_f32_e32 v59, v223, v175
	v_fmac_f32_e32 v60, v227, v174
	v_fmac_f32_e32 v61, v227, v175
	v_fmac_f32_e32 v62, v231, v174
	v_fmac_f32_e32 v63, v231, v175
	s_waitcnt lgkmcnt(0)
	ds_read_b128 v[200:203], v13 offset:240
	ds_read_b128 v[204:207], v13 offset:4336
	ds_read_b128 v[208:211], v13 offset:8432
	ds_read_b128 v[212:215], v13 offset:12528
	ds_read_b128 v[216:219], v13 offset:16624
	ds_read_b128 v[220:223], v13 offset:20720
	ds_read_b128 v[224:227], v13 offset:24816
	ds_read_b128 v[228:231], v13 offset:28912
	s_waitcnt vmcnt(4)
	v_fmac_f32_e32 v48, v16, v176
	v_fmac_f32_e32 v49, v16, v177
	v_fmac_f32_e32 v50, v20, v176
	v_fmac_f32_e32 v51, v20, v177
	v_fmac_f32_e32 v52, v24, v176
	v_fmac_f32_e32 v53, v24, v177
	v_fmac_f32_e32 v54, v28, v176
	v_fmac_f32_e32 v55, v28, v177
	v_fmac_f32_e32 v56, v32, v176
	v_fmac_f32_e32 v57, v32, v177
	v_fmac_f32_e32 v58, v36, v176
	v_fmac_f32_e32 v59, v36, v177
	v_fmac_f32_e32 v60, v40, v176
	v_fmac_f32_e32 v61, v40, v177
	v_fmac_f32_e32 v62, v44, v176
	v_fmac_f32_e32 v63, v44, v177
	v_fmac_f32_e32 v48, v17, v178
	v_fmac_f32_e32 v49, v17, v179
	v_fmac_f32_e32 v50, v21, v178
	v_fmac_f32_e32 v51, v21, v179
	v_fmac_f32_e32 v52, v25, v178
	v_fmac_f32_e32 v53, v25, v179
	v_fmac_f32_e32 v54, v29, v178
	v_fmac_f32_e32 v55, v29, v179
	v_fmac_f32_e32 v56, v33, v178
	v_fmac_f32_e32 v57, v33, v179
	v_fmac_f32_e32 v58, v37, v178
	v_fmac_f32_e32 v59, v37, v179
	v_fmac_f32_e32 v60, v41, v178
	v_fmac_f32_e32 v61, v41, v179
	v_fmac_f32_e32 v62, v45, v178
	v_fmac_f32_e32 v63, v45, v179
	v_fmac_f32_e32 v48, v18, v180
	v_fmac_f32_e32 v49, v18, v181
	v_fmac_f32_e32 v50, v22, v180
	v_fmac_f32_e32 v51, v22, v181
	v_fmac_f32_e32 v52, v26, v180
	v_fmac_f32_e32 v53, v26, v181
	v_fmac_f32_e32 v54, v30, v180
	v_fmac_f32_e32 v55, v30, v181
	v_fmac_f32_e32 v56, v34, v180
	v_fmac_f32_e32 v57, v34, v181
	v_fmac_f32_e32 v58, v38, v180
	v_fmac_f32_e32 v59, v38, v181
	v_fmac_f32_e32 v60, v42, v180
	v_fmac_f32_e32 v61, v42, v181
	v_fmac_f32_e32 v62, v46, v180
	v_fmac_f32_e32 v63, v46, v181
	v_fmac_f32_e32 v48, v19, v182
	v_fmac_f32_e32 v49, v19, v183
	v_fmac_f32_e32 v50, v23, v182
	v_fmac_f32_e32 v51, v23, v183
	v_fmac_f32_e32 v52, v27, v182
	v_fmac_f32_e32 v53, v27, v183
	v_fmac_f32_e32 v54, v31, v182
	v_fmac_f32_e32 v55, v31, v183
	v_fmac_f32_e32 v56, v35, v182
	v_fmac_f32_e32 v57, v35, v183
	v_fmac_f32_e32 v58, v39, v182
	v_fmac_f32_e32 v59, v39, v183
	v_fmac_f32_e32 v60, v43, v182
	v_fmac_f32_e32 v61, v43, v183
	v_fmac_f32_e32 v62, v47, v182
	v_fmac_f32_e32 v63, v47, v183
	s_waitcnt lgkmcnt(0)
	s_waitcnt vmcnt(0)
	v_fmac_f32_e32 v48, v200, v184
	v_fmac_f32_e32 v49, v200, v185
	v_fmac_f32_e32 v50, v204, v184
	v_fmac_f32_e32 v51, v204, v185
	v_fmac_f32_e32 v52, v208, v184
	v_fmac_f32_e32 v53, v208, v185
	v_fmac_f32_e32 v54, v212, v184
	v_fmac_f32_e32 v55, v212, v185
	v_fmac_f32_e32 v56, v216, v184
	v_fmac_f32_e32 v57, v216, v185
	v_fmac_f32_e32 v58, v220, v184
	v_fmac_f32_e32 v59, v220, v185
	v_fmac_f32_e32 v60, v224, v184
	v_fmac_f32_e32 v61, v224, v185
	v_fmac_f32_e32 v62, v228, v184
	v_fmac_f32_e32 v63, v228, v185
	v_fmac_f32_e32 v48, v201, v186
	v_fmac_f32_e32 v49, v201, v187
	v_fmac_f32_e32 v50, v205, v186
	v_fmac_f32_e32 v51, v205, v187
	v_fmac_f32_e32 v52, v209, v186
	v_fmac_f32_e32 v53, v209, v187
	v_fmac_f32_e32 v54, v213, v186
	v_fmac_f32_e32 v55, v213, v187
	v_fmac_f32_e32 v56, v217, v186
	v_fmac_f32_e32 v57, v217, v187
	v_fmac_f32_e32 v58, v221, v186
	v_fmac_f32_e32 v59, v221, v187
	v_fmac_f32_e32 v60, v225, v186
	v_fmac_f32_e32 v61, v225, v187
	v_fmac_f32_e32 v62, v229, v186
	v_fmac_f32_e32 v63, v229, v187
	v_fmac_f32_e32 v48, v202, v188
	v_fmac_f32_e32 v49, v202, v189
	v_fmac_f32_e32 v50, v206, v188
	v_fmac_f32_e32 v51, v206, v189
	v_fmac_f32_e32 v52, v210, v188
	v_fmac_f32_e32 v53, v210, v189
	v_fmac_f32_e32 v54, v214, v188
	v_fmac_f32_e32 v55, v214, v189
	v_fmac_f32_e32 v56, v218, v188
	v_fmac_f32_e32 v57, v218, v189
	v_fmac_f32_e32 v58, v222, v188
	v_fmac_f32_e32 v59, v222, v189
	v_fmac_f32_e32 v60, v226, v188
	v_fmac_f32_e32 v61, v226, v189
	v_fmac_f32_e32 v62, v230, v188
	v_fmac_f32_e32 v63, v230, v189
	v_fmac_f32_e32 v48, v203, v190
	v_fmac_f32_e32 v49, v203, v191
	v_fmac_f32_e32 v50, v207, v190
	v_fmac_f32_e32 v51, v207, v191
	v_fmac_f32_e32 v52, v211, v190
	v_fmac_f32_e32 v53, v211, v191
	v_fmac_f32_e32 v54, v215, v190
	v_fmac_f32_e32 v55, v215, v191
	v_fmac_f32_e32 v56, v219, v190
	v_fmac_f32_e32 v57, v219, v191
	v_fmac_f32_e32 v58, v223, v190
	v_fmac_f32_e32 v59, v223, v191
	v_fmac_f32_e32 v60, v227, v190
	v_fmac_f32_e32 v61, v227, v191
	v_fmac_f32_e32 v62, v231, v190
	v_fmac_f32_e32 v63, v231, v191
	ds_write_b64 v14, v[48:49] offset:0
	ds_write_b64 v14, v[50:51] offset:256
	ds_write_b64 v14, v[52:53] offset:512
	ds_write_b64 v14, v[54:55] offset:768
	ds_write_b64 v14, v[56:57] offset:1024
	ds_write_b64 v14, v[58:59] offset:1280
	ds_write_b64 v14, v[60:61] offset:1536
	ds_write_b64 v14, v[62:63] offset:1792
	s_waitcnt lgkmcnt(0)
	s_barrier
	ds_read2st64_b32 v[16:17], v232 offset0:0 offset1:8
	ds_read2st64_b32 v[18:19], v232 offset0:16 offset1:24
	ds_read2st64_b32 v[20:21], v232 offset0:32 offset1:40
	ds_read2st64_b32 v[22:23], v232 offset0:48 offset1:56
	ds_read2st64_b32 v[24:25], v232 offset0:64 offset1:72
	ds_read2st64_b32 v[26:27], v232 offset0:80 offset1:88
	ds_read2st64_b32 v[28:29], v232 offset0:96 offset1:104
	ds_read2st64_b32 v[30:31], v232 offset0:112 offset1:120
	s_waitcnt vmcnt(0) lgkmcnt(0)
	v_add_f32_e32 v235, v235, v16
	v_add_f32_e32 v235, v235, v17
	v_add_f32_e32 v235, v235, v18
	v_add_f32_e32 v235, v235, v19
	v_add_f32_e32 v235, v235, v20
	v_add_f32_e32 v235, v235, v21
	v_add_f32_e32 v235, v235, v22
	v_add_f32_e32 v235, v235, v23
	v_add_f32_e32 v235, v235, v24
	v_add_f32_e32 v235, v235, v25
	v_add_f32_e32 v235, v235, v26
	v_add_f32_e32 v235, v235, v27
	v_add_f32_e32 v235, v235, v28
	v_add_f32_e32 v235, v235, v29
	v_add_f32_e32 v235, v235, v30
	v_add_f32_e32 v235, v235, v31
	global_store_dword v233, v235, s[10:11]
	s_barrier
